# RET phase: LDS reads batched ahead of MFMA chains (segments B,C,D), vmcnt(3) at loop top
# baseline (speedup 1.0000x reference)
; __device__ __forceinline__ void ret_phase(const Params& p, unsigned char* shm, float* rssq) {
;     ...
;     const float lg = logf(1.0f - exp2f(-5.0f - (float)h));
;     const float cdec = __expf(lg * 64.0f);
;     const int mi = wid >> 1, ni0 = 2 * (wid & 1);
;     const float qdec = __expf(lg * (float)(16 * mi + fr + 1));
;     float idec[2][4];
; #pragma unroll
;     for (int t = 0; t < 2; ++t)
; #pragma unroll
;         for (int j = 0; j < 4; ++j) { const int n = 16 * mi + fr, m = 16 * (ni0 + t) + 4 * fq + j; idec[t][j] = __expf(lg * (fabsf((float)(n - m)) - (float)(63 - m))); }
;     f32x4 R[4][2];
; #pragma unroll
;     for (int a = 0; a < 4; ++a)
; #pragma unroll
;         for (int d = 0; d < 2; ++d) R[a][d] = (f32x4){0.f, 0.f, 0.f, 0.f};
;     const size_t tokb = (size_t)b * S_;
;     const bf16_t* qsrc = ret + (tokb + (tid >> 5)) * 12288 + h * 256 + (tid & 31) * 8;
;     const bf16_t* ksrc = ret + (tokb + lane) * 12288 + 2048 + h * 256 + wid * 32;
;     const bf16_t* vsrc = ret + (tokb + lane) * 12288 + 4096 + h * 512 + sl * 64 + wid * 8;
;     u32x4 pq[4], pk[4], pv; u32x2 pg[2], cg2[2];
;     const bf16_t* gsrc = ret + (tokb + 16 * mi + fr) * 12288 + 8192 + h * 512 + sl * 64 + 16 * ni0 + 4 * fq;
; #pragma unroll
;     for (int j = 0; j < 4; ++j) { pq[j] = *(const u32x4*)(qsrc + (size_t)j * 16 * 12288); pk[j] = *(const u32x4*)(ksrc + j * 8); }
.LBB0_176:
	s_and_b64 vcc, exec, s[0:1]
	s_cbranch_vccz .LBB0_184
	v_readlane_b32 s0, v255, 6
	v_readlane_b32 s1, v255, 7
	s_add_u32 s5, s0, 0x3e820000
	s_waitcnt vmcnt(0)
	v_mov_b32_e32 v1, v228
	v_readlane_b32 s0, v254, 0
	s_addc_u32 s14, s1, 0
	s_lshl_b32 s1, s0, 2
	s_and_b32 s1, s1, 28
	s_ashr_i32 s6, s0, 6
	s_add_i32 s6, s1, s6
	s_and_b32 s15, s6, 7
	v_cvt_f32_ubyte0_e32 v0, s15
	v_sub_f32_e32 v0, 0xc0a00000, v0
	s_mov_b32 s1, 0xc2fc0000
	v_cmp_gt_f32_e32 vcc, s1, v0
	v_mov_b32_e32 v2, 0x42800000
	s_bfe_u32 s17, s0, 0x30003
	v_cndmask_b32_e32 v2, 0, v2, vcc
	v_add_f32_e32 v0, v0, v2
	v_exp_f32_e32 v0, v0
	s_and_b64 s[0:1], vcc, exec
	s_cselect_b32 s0, 0xffffffc0, 0
	v_mov_b32_e32 v2, 0x41b17218
	v_ldexp_f32 v0, v0, s0
	v_sub_f32_e32 v0, 1.0, v0
	v_cmp_gt_f32_e32 vcc, s92, v0
	s_and_b64 s[0:1], vcc, exec
	s_cselect_b32 s0, 32, 0
	v_ldexp_f32 v0, v0, s0
	v_log_f32_e32 v3, v0
	s_mov_b32 s0, 0x3f317217
	v_cndmask_b32_e32 v2, 0, v2, vcc
	v_ashrrev_i32_e32 v54, 6, v1
	v_mul_f32_e32 v4, 0x3f317217, v3
	v_fma_f32 v4, v3, s0, -v4
	v_fmac_f32_e32 v4, 0x3377d1cf, v3
	s_mov_b32 s0, 0x7f800000
	v_fmac_f32_e32 v4, 0x3f317217, v3
	v_cmp_lt_f32_e64 vcc, |v3|, s0
	v_lshlrev_b32_e32 v6, 1, v54
	v_bfe_u32 v52, v1, 4, 2
	v_cndmask_b32_e32 v3, v3, v4, vcc
	v_ashrrev_i32_e32 v4, 3, v1
	v_bfi_b32 v56, -16, v4, v1
	v_add_u32_e32 v5, 1, v56
	v_cvt_f32_i32_e32 v5, v5
	v_and_b32_e32 v53, 2, v6
	v_lshlrev_b32_e32 v136, 2, v52
	v_lshlrev_b32_e32 v101, 4, v53
	v_sub_f32_e32 v2, v3, v2
	v_or_b32_e32 v57, v101, v136
	v_and_b32_e32 v102, -16, v4
	v_mul_f32_e32 v4, v2, v5
	v_sub_u32_e32 v5, v56, v57
	v_cvt_f32_i32_e32 v5, v5
	v_mul_f32_e32 v58, 0x3fb8aa3b, v4
	v_bitop3_b32 v4, v101, 63, v136 bitop3:0x36
	v_cvt_f32_ubyte0_e32 v4, v4
	v_sub_f32_e64 v4, |v5|, v4
	v_xad_u32 v5, v57, -1, v56
	v_mul_f32_e32 v4, v4, v2
	v_cvt_f32_i32_e32 v5, v5
	v_mul_f32_e32 v4, 0x3fb8aa3b, v4
	v_exp_f32_e32 v138, v4
	v_bitop3_b32 v4, v101, 62, v136 bitop3:0x36
	v_cvt_f32_ubyte0_e32 v4, v4
	v_sub_f32_e64 v4, |v5|, v4
	v_add_u32_e32 v5, -2, v56
	v_sub_u32_e32 v6, v5, v57
	v_mul_f32_e32 v4, v4, v2
	v_cvt_f32_i32_e32 v6, v6
	v_mul_f32_e32 v4, 0x3fb8aa3b, v4
	v_exp_f32_e32 v139, v4
	v_bitop3_b32 v4, v101, 61, v136 bitop3:0x36
	v_cvt_f32_ubyte0_e32 v4, v4
	v_sub_f32_e64 v4, |v6|, v4
	v_add_u32_e32 v6, -3, v56
	v_sub_u32_e32 v7, v6, v57
	v_mul_f32_e32 v4, v4, v2
	v_cvt_f32_i32_e32 v7, v7
	v_mul_f32_e32 v4, 0x3fb8aa3b, v4
	v_exp_f32_e32 v140, v4
	v_bitop3_b32 v4, v101, 60, v136 bitop3:0x36
	v_or_b32_e32 v59, 1, v53
	v_cvt_f32_ubyte0_e32 v4, v4
	v_lshlrev_b32_e32 v137, 4, v59
	v_sub_f32_e64 v4, |v7|, v4
	v_or_b32_e32 v7, v137, v136
	v_sub_u32_e32 v8, v56, v7
	v_mul_f32_e32 v4, v4, v2
	v_cvt_f32_i32_e32 v8, v8
	v_mul_f32_e32 v4, 0x3fb8aa3b, v4
	v_exp_f32_e32 v141, v4
	v_bitop3_b32 v4, v137, 63, v136 bitop3:0x36
	v_cvt_f32_ubyte0_e32 v4, v4
	v_sub_f32_e64 v4, |v8|, v4
	v_xad_u32 v8, v7, -1, v56
	v_mul_f32_e32 v4, v2, v4
	v_cvt_f32_i32_e32 v8, v8
	v_mul_f32_e32 v4, 0x3fb8aa3b, v4
	v_exp_f32_e32 v142, v4
	v_bitop3_b32 v4, v137, 62, v136 bitop3:0x36
	v_cvt_f32_ubyte0_e32 v4, v4
	v_sub_f32_e64 v4, |v8|, v4
	v_sub_u32_e32 v5, v5, v7
	v_mul_f32_e32 v4, v2, v4
	v_cvt_f32_i32_e32 v5, v5
	v_mul_f32_e32 v4, 0x3fb8aa3b, v4
	v_exp_f32_e32 v143, v4
	v_bitop3_b32 v4, v137, 61, v136 bitop3:0x36
	v_cvt_f32_ubyte0_e32 v4, v4
	v_sub_f32_e64 v4, |v5|, v4
	v_sub_u32_e32 v5, v6, v7
	v_mul_f32_e32 v4, v2, v4
	v_cvt_f32_i32_e32 v5, v5
	v_mul_f32_e32 v4, 0x3fb8aa3b, v4
	v_exp_f32_e32 v144, v4
	v_bitop3_b32 v4, v137, 60, v136 bitop3:0x36
	v_cvt_f32_ubyte0_e32 v4, v4
	v_sub_f32_e64 v4, |v5|, v4
	v_mul_f32_e32 v3, 0x42800000, v2
	v_mul_f32_e32 v2, v2, v4
	v_mul_f32_e32 v2, 0x3fb8aa3b, v2
	s_ashr_i32 s0, s6, 3
	v_mul_f32_e32 v3, 0x3fb8aa3b, v3
	v_exp_f32_e32 v145, v2
	s_ashr_i32 s1, s0, 31
	v_ashrrev_i32_e32 v2, 5, v1
	v_readlane_b32 s10, v254, 16
	v_exp_f32_e32 v112, v3
	s_lshl_b64 s[6:7], s[0:1], 12
	v_ashrrev_i32_e32 v3, 31, v2
	v_readlane_b32 s11, v254, 17
	v_and_b32_e32 v55, 63, v1
	v_lshl_add_u64 v[4:5], s[6:7], 0, v[2:3]
	v_mov_b64_e32 v[6:7], s[10:11]
	v_lshlrev_b32_e32 v3, 4, v1
	v_mad_u64_u32 v[8:9], s[10:11], v4, s3, v[6:7]
	v_and_b32_e32 v188, 0x1f0, v3
	v_or_b32_e32 v3, s6, v55
	v_mad_i32_i24 v9, v5, s3, v9
	s_lshl_b32 s46, s15, 9
	v_mad_u64_u32 v[22:23], s[10:11], v3, s3, v[6:7]
	v_mov_b32_e32 v3, 0x6000
	v_lshlrev_b32_e32 v40, 5, v54
	v_lshl_add_u64 v[4:5], v[8:9], 0, s[46:47]
	v_mad_i32_i24 v23, s7, v3, v23
	v_ashrrev_i32_e32 v41, 31, v40
	v_lshl_add_u64 v[20:21], v[4:5], 0, v[188:189]
	v_lshl_add_u64 v[4:5], v[22:23], 0, s[46:47]
	v_lshlrev_b64 v[42:43], 1, v[40:41]
	v_lshl_add_u64 v[4:5], v[4:5], 0, v[42:43]
	v_ashrrev_i32_e32 v103, 31, v102
	s_movk_i32 s1, 0x1000
	v_and_b32_e32 v100, 15, v1
	v_lshl_add_u64 v[46:47], s[6:7], 0, v[102:103]
	v_add_co_u32_e32 v24, vcc, s1, v4
	s_mov_b64 s[10:11], 0x1000
	v_or_b32_e32 v46, v46, v100
	v_addc_co_u32_e32 v25, vcc, 0, v5, vcc
	v_lshl_add_u64 v[12:13], v[4:5], 0, s[10:11]
	v_mad_u64_u32 v[48:49], s[10:11], v46, s3, 0
	v_mad_u64_u32 v[6:7], s[10:11], v46, s3, v[6:7]
	v_add_co_u32_e32 v26, vcc, s29, v20
	v_mad_i32_i24 v7, v47, s3, v7
	s_lshl_b32 s10, s15, 10
	s_mov_b32 s11, s47
	v_addc_co_u32_e32 v27, vcc, 0, v21, vcc
	v_lshl_add_u64 v[50:51], v[6:7], 0, s[10:11]
	global_load_dwordx4 v[4:7], v[12:13], off offset:48
	global_load_dwordx4 v[8:11], v[12:13], off offset:32
	global_load_dwordx4 v[16:19], v[20:21], off
	s_nop 0
	global_load_dwordx4 v[12:15], v[12:13], off offset:16
	s_nop 0
	global_load_dwordx4 v[28:31], v[24:25], off
	global_load_dwordx4 v[36:39], v[26:27], off
	v_add_co_u32_e32 v24, vcc, s30, v20
	v_lshlrev_b32_e32 v44, 3, v54
	s_nop 0
; __device__ __forceinline__ void ret_phase(const Params& p, unsigned char* shm, float* rssq) {
;     ...
;     f32x4 R[4][2];
; #pragma unroll
;     for (int a = 0; a < 4; ++a)
; #pragma unroll
;         for (int d = 0; d < 2; ++d) R[a][d] = (f32x4){0.f, 0.f, 0.f, 0.f};
;     const size_t tokb = (size_t)b * S_;
;     const bf16_t* qsrc = ret + (tokb + (tid >> 5)) * 12288 + h * 256 + (tid & 31) * 8;
;     const bf16_t* ksrc = ret + (tokb + lane) * 12288 + 2048 + h * 256 + wid * 32;
;     const bf16_t* vsrc = ret + (tokb + lane) * 12288 + 4096 + h * 512 + sl * 64 + wid * 8;
;     u32x4 pq[4], pk[4], pv; u32x2 pg[2], cg2[2];
;     const bf16_t* gsrc = ret + (tokb + 16 * mi + fr) * 12288 + 8192 + h * 512 + sl * 64 + 16 * ni0 + 4 * fq;
; #pragma unroll
;     for (int j = 0; j < 4; ++j) { pq[j] = *(const u32x4*)(qsrc + (size_t)j * 16 * 12288); pk[j] = *(const u32x4*)(ksrc + j * 8); }
;     pv = *(const u32x4*)vsrc;
;     pg[0] = *(const u32x2*)gsrc; pg[1] = *(const u32x2*)(gsrc + 16);
	v_addc_co_u32_e32 v25, vcc, 0, v21, vcc
	v_add_co_u32_e32 v20, vcc, s31, v20
	v_ashrrev_i32_e32 v45, 31, v44
	s_nop 0
	v_addc_co_u32_e32 v21, vcc, 0, v21, vcc
	global_load_dwordx4 v[32:35], v[24:25], off
	s_nop 0
	global_load_dwordx4 v[24:27], v[20:21], off
	v_lshl_add_u64 v[20:21], v[22:23], 0, s[10:11]
	s_lshl_b32 s12, s17, 7
	s_mov_b32 s13, s47
	v_lshl_add_u64 v[20:21], v[20:21], 0, s[12:13]
	v_lshlrev_b64 v[44:45], 1, v[44:45]
	v_lshl_add_u64 v[20:21], v[20:21], 0, v[44:45]
	v_lshl_add_u64 v[22:23], v[50:51], 0, s[12:13]
	v_lshlrev_b32_e32 v116, 5, v53
	v_mov_b32_e32 v117, v189
	s_movk_i32 s1, 0x2000
	v_lshl_add_u64 v[22:23], v[22:23], 0, v[116:117]
	v_lshlrev_b32_e32 v50, 3, v52
	v_mov_b32_e32 v51, v189
	v_add_co_u32_e32 v20, vcc, s1, v20
	v_lshl_add_u64 v[22:23], v[22:23], 0, v[50:51]
	s_nop 0
	v_addc_co_u32_e32 v21, vcc, 0, v21, vcc
	s_movk_i32 s1, 0x4000
	v_lshl_add_u64 v[52:53], v[22:23], 0, s[90:91]
	v_add_co_u32_e32 v22, vcc, s1, v22
	v_mul_u32_u24_e32 v3, 0x210, v55
	s_nop 0
	v_addc_co_u32_e32 v23, vcc, 0, v23, vcc
	global_load_dwordx2 v[110:111], v[22:23], off
	s_nop 0
	global_load_dwordx4 v[20:23], v[20:21], off
	s_nop 0
	global_load_dwordx2 v[108:109], v[52:53], off offset:32
	v_and_b32_e32 v41, 0xffffffc0, v1
	v_readlane_b32 s11, v254, 50
	s_movk_i32 s1, 0x210
	v_add3_u32 v150, 0, v3, v41
	v_add3_u32 v51, s11, v41, v50
	v_mul_lo_u32 v41, v56, s1
	s_movk_i32 s18, 0x90
	v_add_u32_e32 v52, 0, v41
	v_mul_lo_u32 v41, v56, s18
	v_readlane_b32 s13, v254, 51
	v_and_b32_e32 v53, 48, v1
	v_mul_lo_u32 v60, v2, s1
	v_add_u32_e32 v41, s13, v41
	s_movk_i32 s1, 0x1200
	v_lshlrev_b32_e32 v3, 1, v55
	v_add_u32_e32 v172, v41, v50
	v_add_u32_e32 v117, v41, v53
	v_add_u32_e32 v176, s11, v53
	v_readlane_b32 s11, v254, 48
	v_mul_lo_u32 v41, v54, s1
	s_movk_i32 s1, 0x480
	v_readlane_b32 s13, v254, 49
	v_add3_u32 v151, s11, v3, v41
	v_add3_u32 v175, s11, v41, v3
	v_mul_lo_u32 v41, v54, s1
	s_lshl_b32 s16, s17, 6
	v_add_u32_e32 v56, s13, v53
	v_add3_u32 v152, s13, v3, v41
	v_add3_u32 v160, s13, v41, v3
	s_lshl_b32 s13, s17, 19
	s_lshl_b32 s1, s15, 2
	s_add_u32 s1, s5, s1
	v_exp_f32_e32 v104, v58
	v_or_b32_e32 v40, v40, v100
	v_add_u32_e32 v58, s11, v53
	s_addc_u32 s11, s14, 0
	v_or_b32_e32 v41, v137, v100
	v_mul_lo_u32 v63, v40, s18
	s_add_u32 s18, s1, s13
	v_mul_u32_u24_e32 v178, 0x210, v41
	v_mul_u32_u24_e32 v62, 0x90, v41
	v_lshlrev_b64 v[40:41], 5, v[46:47]
	s_addc_u32 s19, s11, 0
	v_lshl_add_u64 v[120:121], s[18:19], 0, v[40:41]
	v_lshlrev_b64 v[40:41], 13, v[46:47]
	v_or_b32_e32 v3, v101, v100
	v_or_b32_e32 v40, s10, v40
	s_mov_b64 s[18:19], 0x35000000
	v_mul_u32_u24_e32 v177, 0x210, v3
	v_mul_u32_u24_e32 v61, 0x90, v3
	v_lshl_add_u64 v[40:41], v[40:41], 0, s[18:19]
	v_or3_b32 v3, s16, v101, v136
	v_lshl_or_b32 v122, v3, 1, v40
	v_or_b32_e32 v3, s16, v57
	v_mad_i32_i24 v115, v47, s3, v49
	v_add_u32_e32 v49, 0, v188
	v_lshl_or_b32 v188, v3, 1, 32
	v_lshl_add_u64 v[124:125], v[40:41], 0, v[188:189]
	v_mad_i64_i32 v[2:3], s[18:19], v2, s3, 0
	v_mov_b32_e32 v40, 0x6000000
	s_mul_hi_i32 s11, s0, 0x6000000
	s_mul_i32 s17, s0, 0x6000000
	v_mad_i64_i32 v[126:127], s[0:1], s0, v40, v[2:3]
	v_and_b32_e32 v2, 31, v1
	v_lshlrev_b32_e32 v2, 4, v2
	v_or3_b32 v126, v126, s46, v2
	v_or_b32_e32 v2, s10, v48
	s_add_u32 s0, s17, 0x1d181020
	v_or_b32_e32 v2, s12, v2
	v_and_b32_e32 v1, 64, v1
	s_addc_u32 s1, s11, 0
	v_or3_b32 v114, v2, v1, v50
	v_mov_b64_e32 v[2:3], s[0:1]
	v_mad_u64_u32 v[2:3], s[0:1], v55, s3, v[2:3]
	s_add_u32 s0, s17, 0x1d182000
	v_or_b32_e32 v2, s46, v2
	s_addc_u32 s1, s11, 0
	v_lshl_add_u64 v[128:129], v[2:3], 0, v[42:43]
	v_mov_b64_e32 v[2:3], s[0:1]
	v_mad_u64_u32 v[2:3], s[0:1], v55, s3, v[2:3]
	v_or_b32_e32 v1, s10, v2
	v_mov_b32_e32 v0, 0
	v_mul_u32_u24_e32 v54, 0x210, v100
	v_lshlrev_b32_e32 v59, 5, v59
	v_mul_u32_u24_e32 v64, 0x90, v100
	v_or_b32_e32 v2, s12, v1
	v_add_u32_e32 v168, 0, v53
	v_mov_b32_e32 v105, v104
	v_mov_b32_e32 v106, v104
	v_mov_b32_e32 v107, v104
	v_cmp_gt_u32_e32 vcc, 16, v55
	v_mov_b32_e32 v118, v112
	v_mov_b32_e32 v119, v112
	v_add_u32_e32 v174, 0x120, v151
	v_add_u32_e32 v173, 0x240, v151
	v_add_u32_e32 v171, 0x360, v151
	v_add_u32_e32 v170, 0x480, v151
	v_add_u32_e32 v169, 0x5a0, v151
	v_add_u32_e32 v167, 0x6c0, v151
	v_add_u32_e32 v166, 0x7e0, v151
	v_add_u32_e32 v164, 0x900, v151
	v_add_u32_e32 v163, 0xa20, v151
	v_add_u32_e32 v162, 0xb40, v151
	v_add_u32_e32 v161, 0xc60, v151
	v_add_u32_e32 v159, 0xd80, v151
	v_add_u32_e32 v157, 0xea0, v151
	v_add_u32_e32 v155, 0xfc0, v151
	v_add_u32_e32 v153, 0x10e0, v151
	v_add_u32_e32 v158, 0x120, v152
	v_add_u32_e32 v156, 0x240, v152
	v_add_u32_e32 v154, 0x360, v152
	v_mov_b32_e32 v123, v41
	v_lshl_add_u64 v[130:131], v[2:3], 0, v[44:45]
	s_mov_b64 s[10:11], 0
	v_add_u32_e32 v180, v58, v63
	v_add_u32_e32 v181, v56, v64
	v_add_u32_e32 v179, v49, v60
	v_add_u32_e32 v165, v51, v54
	v_add_u32_e32 v149, v52, v53
	v_add_u32_e32 v148, v172, v59
	v_add_u32_e32 v147, v56, v61
	v_add_u32_e32 v146, v56, v62
	v_mov_b32_e32 v1, v0
	v_mov_b32_e32 v2, v0
	v_mov_b32_e32 v3, v0
	v_mov_b32_e32 v64, v0
	v_mov_b32_e32 v65, v0
	v_mov_b32_e32 v66, v0
	v_mov_b32_e32 v67, v0
	v_mov_b32_e32 v48, v0
	v_mov_b32_e32 v49, v0
	v_mov_b32_e32 v50, v0
	v_mov_b32_e32 v51, v0
	v_mov_b32_e32 v60, v0
	v_mov_b32_e32 v61, v0
	v_mov_b32_e32 v62, v0
	v_mov_b32_e32 v63, v0
	v_mov_b32_e32 v44, v0
	v_mov_b32_e32 v45, v0
	v_mov_b32_e32 v46, v0
	v_mov_b32_e32 v47, v0
	v_mov_b32_e32 v56, v0
	v_mov_b32_e32 v57, v0
	v_mov_b32_e32 v58, v0
	v_mov_b32_e32 v59, v0
	v_mov_b32_e32 v40, v0
	v_mov_b32_e32 v41, v0
	v_mov_b32_e32 v42, v0
	v_mov_b32_e32 v43, v0
	v_mov_b32_e32 v52, v0
	v_mov_b32_e32 v53, v0
	v_mov_b32_e32 v54, v0
	v_mov_b32_e32 v55, v0
	s_mov_b64 s[20:21], 0x80000
	s_waitcnt vmcnt(0)
	s_branch .LBB0_179
; __device__ __forceinline__ void ret_phase(const Params& p, unsigned char* shm, float* rssq) {
;     ...
;     for (int ch = 0; ch < 64; ++ch) {
;         __syncthreads();
;         cg2[0] = pg[0]; cg2[1] = pg[1];
; #pragma unroll
;         for (int j = 0; j < 4; ++j) {
;             *(u32x4*)(Qs + (j * 16 + (tid >> 5)) * QS + (tid & 31) * 8) = pq[j];
;             *(u32x4*)(Ks + lane * QS + wid * 32 + j * 8) = pk[j];
;             const unsigned kw[4] = {pk[j].x, pk[j].y, pk[j].z, pk[j].w};
; #pragma unroll
;             for (int i = 0; i < 4; ++i) {
;                 KTs[(wid * 32 + j * 8 + 2 * i) * TS + lane] = (bf16_t)(kw[i] & 0xffffu);
;                 KTs[(wid * 32 + j * 8 + 2 * i + 1) * TS + lane] = (bf16_t)(kw[i] >> 16);
;             }
;         }
;         { const unsigned vw[4] = {pv.x, pv.y, pv.z, pv.w};
; #pragma unroll
;           for (int i = 0; i < 4; ++i) { VTs[(wid * 8 + 2 * i) * TS + lane] = (bf16_t)(vw[i] & 0xffffu); VTs[(wid * 8 + 2 * i + 1) * TS + lane] = (bf16_t)(vw[i] >> 16); } }
;     ...
; #pragma unroll
;         for (int ei = 0; ei < 4; ++ei)
; #pragma unroll
;             for (int di = 0; di < 2; ++di) R[ei][di] *= cdec;
; #pragma unroll
;         for (int ks = 0; ks < 2; ++ks) {
;             bf16x8 bfk[2];
; #pragma unroll
;             for (int di = 0; di < 2; ++di) bfk[di] = *(const bf16x8*)(KTs + (wid * 32 + 16 * di + fr) * TS + ks * 32 + fq * 8);
; #pragma unroll
;             for (int ei = 0; ei < 4; ++ei) { const bf16x8 af = *(const bf16x8*)(VTs + (16 * ei + fr) * TS + ks * 32 + fq * 8);
; #pragma unroll
;                 for (int di = 0; di < 2; ++di) R[ei][di] = __builtin_amdgcn_mfma_f32_16x16x32_bf16(bfk[di], af, R[ei][di], 0, 0, 0); }
;         }
.LBB0_178:
	s_or_b64 exec, exec, s[0:1]
	s_waitcnt lgkmcnt(0)
	ds_read_b128 v[70:73], v180
	ds_read_b128 v[74:77], v180 offset:2304
	ds_read_b128 v[78:81], v181
	ds_read_b128 v[216:219], v181 offset:2304
	ds_read_b128 v[220:223], v181 offset:4608
	ds_read_b128 v[224:227], v181 offset:6912
	ds_read_b128 v[208:211], v180 offset:64
	ds_read_b128 v[212:215], v180 offset:2368
	ds_read_b128 v[236:239], v181 offset:64
	ds_read_b128 v[240:243], v181 offset:2368
	ds_read_b128 v[244:247], v181 offset:4672
	ds_read_b128 v[248:251], v181 offset:6976
	v_mov_b32_e32 v113, v112
	v_pk_mul_f32 v[54:55], v[112:113], v[54:55]
	v_pk_mul_f32 v[52:53], v[118:119], v[52:53]
	v_pk_mul_f32 v[42:43], v[112:113], v[42:43]
	v_pk_mul_f32 v[40:41], v[118:119], v[40:41]
	v_mul_f32_e64 v58, v112, v58
	v_mul_f32_e64 v59, v113, v59
	v_pk_mul_f32 v[56:57], v[118:119], v[56:57]
	v_pk_mul_f32 v[46:47], v[112:113], v[46:47]
	v_pk_mul_f32 v[44:45], v[118:119], v[44:45]
	v_pk_mul_f32 v[62:63], v[112:113], v[62:63]
	v_mul_f32_e64 v60, v118, v60
	v_mul_f32_e64 v61, v119, v61
	v_pk_mul_f32 v[50:51], v[112:113], v[50:51]
	v_pk_mul_f32 v[48:49], v[118:119], v[48:49]
	v_pk_mul_f32 v[66:67], v[112:113], v[66:67]
	v_pk_mul_f32 v[64:65], v[118:119], v[64:65]
	v_mul_f32_e64 v2, v112, v2
	v_mul_f32_e64 v3, v113, v3
	v_pk_mul_f32 v[0:1], v[118:119], v[0:1]
	s_nop 1
	s_waitcnt lgkmcnt(9)
	v_mfma_f32_16x16x32_bf16 v[52:55], v[70:73], v[78:81], v[52:55]
	v_mfma_f32_16x16x32_bf16 v[40:43], v[74:77], v[78:81], v[40:43]
	s_add_u32 s10, s10, 0x800
	s_addc_u32 s11, s11, 0
	s_waitcnt lgkmcnt(8)
	v_mfma_f32_16x16x32_bf16 v[56:59], v[70:73], v[216:219], v[56:59]
	v_mfma_f32_16x16x32_bf16 v[44:47], v[74:77], v[216:219], v[44:47]
	v_lshl_add_u64 v[122:123], v[122:123], 0, s[20:21]
	v_lshl_add_u64 v[124:125], v[124:125], 0, s[20:21]
	s_waitcnt lgkmcnt(7)
	v_mfma_f32_16x16x32_bf16 v[60:63], v[70:73], v[220:223], v[60:63]
	v_mfma_f32_16x16x32_bf16 v[48:51], v[74:77], v[220:223], v[48:51]
	v_lshl_add_u64 v[126:127], v[126:127], 0, s[94:95]
	v_lshl_add_u64 v[114:115], v[114:115], 0, s[94:95]
	s_waitcnt lgkmcnt(6)
	v_mfma_f32_16x16x32_bf16 v[64:67], v[70:73], v[224:227], v[64:67]
	v_mfma_f32_16x16x32_bf16 v[0:3], v[74:77], v[224:227], v[0:3]
	v_lshl_add_u64 v[128:129], v[128:129], 0, s[94:95]
	v_lshl_add_u64 v[130:131], v[130:131], 0, s[94:95]
	s_waitcnt lgkmcnt(3)
	v_mfma_f32_16x16x32_bf16 v[52:55], v[208:211], v[236:239], v[52:55]
	v_mfma_f32_16x16x32_bf16 v[40:43], v[212:215], v[236:239], v[40:43]
	s_cmp_eq_u32 s10, 0x1f800
	s_waitcnt lgkmcnt(2)
	v_mfma_f32_16x16x32_bf16 v[56:59], v[208:211], v[240:243], v[56:59]
	v_mfma_f32_16x16x32_bf16 v[44:47], v[212:215], v[240:243], v[44:47]
	s_waitcnt lgkmcnt(1)
	v_mfma_f32_16x16x32_bf16 v[60:63], v[208:211], v[244:247], v[60:63]
	v_mfma_f32_16x16x32_bf16 v[48:51], v[212:215], v[244:247], v[48:51]
	s_waitcnt lgkmcnt(0)
	v_mfma_f32_16x16x32_bf16 v[64:67], v[208:211], v[248:251], v[64:67]
	v_mfma_f32_16x16x32_bf16 v[0:3], v[212:215], v[248:251], v[0:3]
	s_cbranch_scc1 .LBB0_181
.LBB0_179:
	s_barrier
	s_waitcnt vmcnt(3)
	ds_write_b128 v179, v[16:19]
	s_waitcnt vmcnt(6)
	ds_write_b128 v150, v[28:31] offset:33792
	ds_write_b16 v151, v28
	ds_write_b16_d16_hi v175, v28 offset:144
	ds_write_b16 v151, v29 offset:288
	ds_write_b16_d16_hi v174, v29 offset:144
	ds_write_b16 v151, v30 offset:576
	ds_write_b16_d16_hi v173, v30 offset:144
	ds_write_b16 v151, v31 offset:864
	ds_write_b16_d16_hi v171, v31 offset:144
	s_waitcnt vmcnt(5)
	ds_write_b128 v179, v[36:39] offset:8448
	ds_write_b128 v150, v[12:15] offset:33808
	ds_write_b16 v151, v12 offset:1152
	ds_write_b16_d16_hi v170, v12 offset:144
	ds_write_b16 v151, v13 offset:1440
	ds_write_b16_d16_hi v169, v13 offset:144
	ds_write_b16 v151, v14 offset:1728
	ds_write_b16_d16_hi v167, v14 offset:144
	ds_write_b16 v151, v15 offset:2016
	ds_write_b16_d16_hi v166, v15 offset:144
	s_waitcnt vmcnt(4)
	ds_write_b128 v179, v[32:35] offset:16896
	ds_write_b128 v150, v[8:11] offset:33824
	ds_write_b16 v151, v8 offset:2304
	ds_write_b16_d16_hi v164, v8 offset:144
	ds_write_b16 v151, v9 offset:2592
	ds_write_b16_d16_hi v163, v9 offset:144
	ds_write_b16 v151, v10 offset:2880
	ds_write_b16_d16_hi v162, v10 offset:144
	ds_write_b16 v151, v11 offset:3168
	ds_write_b16_d16_hi v161, v11 offset:144
	s_waitcnt vmcnt(3)
	ds_write_b128 v179, v[24:27] offset:25344
	ds_write_b128 v150, v[4:7] offset:33840
	ds_write_b16 v151, v4 offset:3456
	ds_write_b16_d16_hi v159, v4 offset:144
	ds_write_b16 v151, v5 offset:3744
	ds_write_b16_d16_hi v157, v5 offset:144
	ds_write_b16 v151, v6 offset:4032
	ds_write_b16_d16_hi v155, v6 offset:144
	ds_write_b16 v151, v7 offset:4320
	ds_write_b16_d16_hi v153, v7 offset:144
	s_waitcnt vmcnt(1)
; __device__ __forceinline__ unsigned cvt_pk_bf16(float lo, float hi) { unsigned r; asm volatile("v_cvt_pk_bf16_f32 %0, %1, %2" : "=v"(r) : "v"(lo), "v"(hi)); return r; }
; __device__ __forceinline__ void ret_phase(const Params& p, unsigned char* shm, float* rssq) {
;     ...
;         { const unsigned vw[4] = {pv.x, pv.y, pv.z, pv.w};
; #pragma unroll
;           for (int i = 0; i < 4; ++i) { VTs[(wid * 8 + 2 * i) * TS + lane] = (bf16_t)(vw[i] & 0xffffu); VTs[(wid * 8 + 2 * i + 1) * TS + lane] = (bf16_t)(vw[i] >> 16); } }
; #pragma unroll
;         for (int ei = 0; ei < 4; ++ei)
; #pragma unroll
;             for (int di = 0; di < 2; ++di) { u32x2 w; w.x = cvt_pk_bf16(R[ei][di][0], R[ei][di][1]); w.y = cvt_pk_bf16(R[ei][di][2], R[ei][di][3]);
;                 *(u32x2*)(RTs + (16 * ei + fr) * QS + wid * 32 + 16 * di + 4 * fq) = w; }
;         if (ch + 1 < 64) {
;             const size_t adv = (size_t)(ch + 1) * 64 * 12288;
; #pragma unroll
;             for (int j = 0; j < 4; ++j) { pq[j] = *(const u32x4*)(qsrc + adv + (size_t)j * 16 * 12288); pk[j] = *(const u32x4*)(ksrc + adv + j * 8); }
;             pv = *(const u32x4*)(vsrc + adv);
;             pg[0] = *(const u32x2*)(gsrc + adv); pg[1] = *(const u32x2*)(gsrc + adv + 16);
;         }
;         __syncthreads();
;         bf16x8 qa[8];
;         {
;             f32x4 sacc[2] = {{0.f, 0.f, 0.f, 0.f}, {0.f, 0.f, 0.f, 0.f}};
; #pragma unroll
;             for (int ks = 0; ks < 8; ++ks) qa[ks] = *(const bf16x8*)(Qs + (16 * mi + fr) * QS + ks * 32 + fq * 8);
; #pragma unroll
;             for (int ks = 0; ks < 8; ++ks) {
; #pragma unroll
;                 for (int t = 0; t < 2; ++t) { const bf16x8 bf = *(const bf16x8*)(Ks + (16 * (ni0 + t) + fr) * QS + ks * 32 + fq * 8);
;                     sacc[t] = __builtin_amdgcn_mfma_f32_16x16x32_bf16(bf, qa[ks], sacc[t], 0, 0, 0); }
;             }
; #pragma unroll
;             for (int t = 0; t < 2; ++t) { u32x2 w; w.x = cvt_pk_bf16(sacc[t][0] * idec[t][0], sacc[t][1] * idec[t][1]); w.y = cvt_pk_bf16(sacc[t][2] * idec[t][2], sacc[t][3] * idec[t][3]);
;                 *(u32x2*)(Ss + (16 * mi + fr) * TS + 16 * (ni0 + t) + 4 * fq) = w; }
;         }
	ds_write_b16 v152, v20
	ds_write_b16_d16_hi v160, v20 offset:144
	ds_write_b16 v152, v21 offset:288
	ds_write_b16_d16_hi v158, v21 offset:144
	ds_write_b16 v152, v22 offset:576
	ds_write_b16_d16_hi v156, v22 offset:144
	ds_write_b16 v152, v23 offset:864
	ds_write_b16_d16_hi v154, v23 offset:144
	v_cvt_pk_bf16_f32 v4, v52, v53
	v_cvt_pk_bf16_f32 v5, v54, v55
	ds_write_b64 v165, v[4:5]
	v_cvt_pk_bf16_f32 v4, v40, v41
	v_cvt_pk_bf16_f32 v5, v42, v43
	ds_write_b64 v165, v[4:5] offset:32
	v_cvt_pk_bf16_f32 v4, v56, v57
	v_cvt_pk_bf16_f32 v5, v58, v59
	ds_write_b64 v165, v[4:5] offset:8448
	v_cvt_pk_bf16_f32 v4, v44, v45
	v_cvt_pk_bf16_f32 v5, v46, v47
	ds_write_b64 v165, v[4:5] offset:8480
	v_cvt_pk_bf16_f32 v4, v60, v61
	v_cvt_pk_bf16_f32 v5, v62, v63
	ds_write_b64 v165, v[4:5] offset:16896
	v_cvt_pk_bf16_f32 v4, v48, v49
	v_cvt_pk_bf16_f32 v5, v50, v51
	ds_write_b64 v165, v[4:5] offset:16928
	v_cvt_pk_bf16_f32 v4, v64, v65
	v_cvt_pk_bf16_f32 v5, v66, v67
	ds_write_b64 v165, v[4:5] offset:25344
	v_cvt_pk_bf16_f32 v4, v0, v1
	v_lshl_add_u64 v[20:21], s[56:57], 0, v[126:127]
	s_mov_b32 s0, 0x1d180000
	v_cvt_pk_bf16_f32 v5, v2, v3
	ds_write_b64 v165, v[4:5] offset:25376
	v_add_co_u32_e64 v4, s[0:1], s0, v20
	v_lshl_add_u64 v[22:23], s[56:57], 0, v[128:129]
	s_nop 0
	v_addc_co_u32_e64 v5, s[0:1], 0, v21, s[0:1]
	s_mov_b32 s0, 0x1d1e0000
	global_load_dwordx4 v[16:19], v[4:5], off
	s_nop 0
	global_load_dwordx4 v[4:7], v[22:23], off offset:16
	global_load_dwordx4 v[8:11], v[22:23], off
	global_load_dwordx4 v[12:15], v[22:23], off offset:-16
	global_load_dwordx4 v[28:31], v[22:23], off offset:-32
	v_add_co_u32_e64 v22, s[0:1], s0, v20
	v_lshl_add_u64 v[68:69], s[56:57], 0, v[114:115]
	s_nop 0
	v_addc_co_u32_e64 v23, s[0:1], 0, v21, s[0:1]
	s_mov_b32 s0, 0x1d240000
	global_load_dwordx4 v[36:39], v[22:23], off
	v_add_co_u32_e64 v22, s[0:1], s0, v20
	v_add_u32_e32 v183, v168, v177
	s_nop 0
	v_addc_co_u32_e64 v23, s[0:1], 0, v21, s[0:1]
	s_mov_b32 s0, 0x1d2a0000
	s_nop 0
	v_add_co_u32_e64 v20, s[0:1], s0, v20
	global_load_dwordx4 v[32:35], v[22:23], off
	s_nop 0
	v_addc_co_u32_e64 v21, s[0:1], 0, v21, s[0:1]
	s_mov_b32 s0, 0x1d184000
	s_nop 0
	v_add_co_u32_e64 v68, s[0:1], s0, v68
	global_load_dwordx4 v[24:27], v[20:21], off
	v_lshl_add_u64 v[20:21], s[56:57], 0, v[130:131]
	v_addc_co_u32_e64 v69, s[0:1], 0, v69, s[0:1]
	v_mov_b64_e32 v[134:135], v[110:111]
	s_waitcnt vmcnt(8)
	v_mov_b64_e32 v[132:133], v[108:109]
	global_load_dwordx4 v[20:23], v[20:21], off
	s_nop 0
	global_load_dwordx2 v[110:111], v[68:69], off
	global_load_dwordx2 v[108:109], v[68:69], off offset:32
	s_waitcnt lgkmcnt(0)
	s_barrier
	ds_read_b128 v[96:99], v149
	ds_read_b128 v[92:95], v149 offset:64
	ds_read_b128 v[88:91], v149 offset:128
	ds_read_b128 v[84:87], v149 offset:192
	ds_read_b128 v[80:83], v149 offset:256
	ds_read_b128 v[76:79], v149 offset:320
	ds_read_b128 v[72:75], v149 offset:384
	ds_read_b128 v[68:71], v149 offset:448
	v_add_u32_e32 v182, v168, v178
	ds_read_b128 v[208:211], v183 offset:33792
	ds_read_b128 v[212:215], v182 offset:33792
	ds_read_b128 v[216:219], v183 offset:33856
	ds_read_b128 v[220:223], v182 offset:33856
	ds_read_b128 v[224:227], v183 offset:33920
	ds_read_b128 v[236:239], v182 offset:33920
	ds_read_b128 v[240:243], v183 offset:33984
	s_waitcnt lgkmcnt(6)
	v_mfma_f32_16x16x32_bf16 v[184:187], v[208:211], v[96:99], 0
	ds_read_b128 v[244:247], v182 offset:33984
	s_waitcnt lgkmcnt(6)
	v_mfma_f32_16x16x32_bf16 v[192:195], v[212:215], v[96:99], 0
	ds_read_b128 v[208:211], v183 offset:34048
	s_waitcnt lgkmcnt(6)
	v_mfma_f32_16x16x32_bf16 v[184:187], v[216:219], v[92:95], v[184:187]
	ds_read_b128 v[212:215], v182 offset:34048
	s_waitcnt lgkmcnt(6)
	v_mfma_f32_16x16x32_bf16 v[192:195], v[220:223], v[92:95], v[192:195]
	ds_read_b128 v[216:219], v183 offset:34112
	s_waitcnt lgkmcnt(6)
	v_mfma_f32_16x16x32_bf16 v[184:187], v[224:227], v[88:91], v[184:187]
	ds_read_b128 v[220:223], v182 offset:34112
	s_waitcnt lgkmcnt(6)
	v_mfma_f32_16x16x32_bf16 v[192:195], v[236:239], v[88:91], v[192:195]
	ds_read_b128 v[224:227], v183 offset:34176
	s_waitcnt lgkmcnt(6)
	v_mfma_f32_16x16x32_bf16 v[184:187], v[240:243], v[84:87], v[184:187]
	ds_read_b128 v[236:239], v182 offset:34176
	s_waitcnt lgkmcnt(6)
	v_mfma_f32_16x16x32_bf16 v[192:195], v[244:247], v[84:87], v[192:195]
	ds_read_b128 v[240:243], v183 offset:34240
	s_waitcnt lgkmcnt(6)
	v_mfma_f32_16x16x32_bf16 v[184:187], v[208:211], v[80:83], v[184:187]
	ds_read_b128 v[244:247], v182 offset:34240
	s_waitcnt lgkmcnt(6)
	v_mfma_f32_16x16x32_bf16 v[192:195], v[212:215], v[80:83], v[192:195]
	s_waitcnt lgkmcnt(5)
	v_mfma_f32_16x16x32_bf16 v[184:187], v[216:219], v[76:79], v[184:187]
	s_waitcnt lgkmcnt(4)
	v_mfma_f32_16x16x32_bf16 v[192:195], v[220:223], v[76:79], v[192:195]
	s_waitcnt lgkmcnt(3)
	v_mfma_f32_16x16x32_bf16 v[184:187], v[224:227], v[72:75], v[184:187]
	s_waitcnt lgkmcnt(2)
	v_mfma_f32_16x16x32_bf16 v[192:195], v[236:239], v[72:75], v[192:195]
	s_waitcnt lgkmcnt(1)
	v_mfma_f32_16x16x32_bf16 v[184:187], v[240:243], v[68:71], v[184:187]
	s_waitcnt lgkmcnt(0)
	v_mfma_f32_16x16x32_bf16 v[192:195], v[244:247], v[68:71], v[192:195]
	s_nop 7
	v_mul_f32_e32 v113, v138, v184
	v_mul_f32_e32 v184, v139, v185
	v_mul_f32_e32 v185, v141, v187
	v_cvt_pk_bf16_f32 v184, v113, v184
	v_mul_f32_e32 v113, v140, v186
	v_cvt_pk_bf16_f32 v185, v113, v185
	v_add_u32_e32 v186, v172, v116
	ds_write_b64 v186, v[184:185]
	s_nop 2
	v_mul_f32_e32 v113, v142, v192
	v_mul_f32_e32 v184, v143, v193
	v_mul_f32_e32 v185, v145, v195
	v_cvt_pk_bf16_f32 v184, v113, v184
	v_mul_f32_e32 v113, v144, v194
	v_cvt_pk_bf16_f32 v185, v113, v185
	ds_write_b64 v148, v[184:185]
	s_waitcnt lgkmcnt(0)
	s_barrier
; __device__ __forceinline__ unsigned cvt_pk_bf16(float lo, float hi) { unsigned r; asm volatile("v_cvt_pk_bf16_f32 %0, %1, %2" : "=v"(r) : "v"(lo), "v"(hi)); return r; }
; __device__ __forceinline__ float bflo(unsigned w) { return __uint_as_float(w << 16); }
; __device__ __forceinline__ float bfhi(unsigned w) { return __uint_as_float(w & 0xffff0000u); }
; __device__ __forceinline__ void ret_phase(const Params& p, unsigned char* shm, float* rssq) {
;     ...
;         {
;             f32x4 oi[2] = {{0.f, 0.f, 0.f, 0.f}, {0.f, 0.f, 0.f, 0.f}}, oc[2] = {{0.f, 0.f, 0.f, 0.f}, {0.f, 0.f, 0.f, 0.f}};
; #pragma unroll
;             for (int ks = 0; ks < 2; ++ks) {
;                 const bf16x8 af = *(const bf16x8*)(Ss + (16 * mi + fr) * TS + ks * 32 + fq * 8);
; #pragma unroll
;                 for (int t = 0; t < 2; ++t) { const bf16x8 bf = *(const bf16x8*)(VTs + (16 * (ni0 + t) + fr) * TS + ks * 32 + fq * 8);
;                     oi[t] = __builtin_amdgcn_mfma_f32_16x16x32_bf16(bf, af, oi[t], 0, 0, 0); }
;             }
; #pragma unroll
;             for (int ks = 0; ks < 8; ++ks) {
; #pragma unroll
;                 for (int t = 0; t < 2; ++t) { const bf16x8 bf = *(const bf16x8*)(RTs + (16 * (ni0 + t) + fr) * QS + ks * 32 + fq * 8);
;                     oc[t] = __builtin_amdgcn_mfma_f32_16x16x32_bf16(bf, qa[ks], oc[t], 0, 0, 0); }
;             }
;             const size_t tok = tokb + (size_t)ch * 64 + 16 * mi + fr;
;             float sq = 0.f;
; #pragma unroll
;             for (int t = 0; t < 2; ++t) {
;                 const int e = sl * 64 + 16 * (ni0 + t) + 4 * fq;
;                 const u32x2 gw = cg2[t];
;                 f32x4 ov = oi[t] + oc[t] * qdec;
;                 sq += ov[0] * ov[0] + ov[1] * ov[1] + ov[2] * ov[2] + ov[3] * ov[3];
;                 u32x2 w; w.x = cvt_pk_bf16(ov[0] * bflo(gw.x), ov[1] * bfhi(gw.x)); w.y = cvt_pk_bf16(ov[2] * bflo(gw.y), ov[3] * bfhi(gw.y));
;                 *(u32x2*)(ao + tok * 4096 + h * 512 + e) = w;
;             }
;             sq += __shfl_xor(sq, 16); sq += __shfl_xor(sq, 32);
;             if (fq == 0) atomicAdd(rssq + (size_t)(sl * 4 + mi) * 0 + (size_t)sl * (T_ * 8) + tok * 8 + h, sq);
	v_add_u32_e32 v185, v176, v177
	v_add_u32_e32 v184, v176, v178
	ds_read_b128 v[200:203], v117
	ds_read_b128 v[208:211], v147
	ds_read_b128 v[212:215], v146
	ds_read_b128 v[204:207], v117 offset:64
	ds_read_b128 v[216:219], v147 offset:64
	ds_read_b128 v[220:223], v146 offset:64
	ds_read_b128 v[224:227], v185
	ds_read_b128 v[236:239], v184
	s_waitcnt lgkmcnt(6)
	v_mfma_f32_16x16x32_bf16 v[196:199], v[208:211], v[200:203], 0
	ds_read_b128 v[240:243], v185 offset:64
	s_waitcnt lgkmcnt(6)
	v_mfma_f32_16x16x32_bf16 v[192:195], v[212:215], v[200:203], 0
	ds_read_b128 v[244:247], v184 offset:64
	ds_read_b128 v[208:211], v185 offset:128
	s_waitcnt lgkmcnt(6)
	v_mfma_f32_16x16x32_bf16 v[196:199], v[216:219], v[204:207], v[196:199]
	ds_read_b128 v[212:215], v184 offset:128
	s_waitcnt lgkmcnt(6)
	v_mfma_f32_16x16x32_bf16 v[192:195], v[220:223], v[204:207], v[192:195]
	ds_read_b128 v[216:219], v185 offset:192
	s_waitcnt lgkmcnt(6)
	v_mfma_f32_16x16x32_bf16 v[248:251], v[224:227], v[96:99], 0
	ds_read_b128 v[220:223], v184 offset:192
	s_waitcnt lgkmcnt(6)
	v_mfma_f32_16x16x32_bf16 v[230:233], v[236:239], v[96:99], 0
	ds_read_b128 v[224:227], v185 offset:256
	s_waitcnt lgkmcnt(6)
	v_mfma_f32_16x16x32_bf16 v[248:251], v[240:243], v[92:95], v[248:251]
	ds_read_b128 v[236:239], v184 offset:256
	s_waitcnt lgkmcnt(6)
	v_mfma_f32_16x16x32_bf16 v[230:233], v[244:247], v[92:95], v[230:233]
	ds_read_b128 v[240:243], v185 offset:320
	s_waitcnt lgkmcnt(6)
	v_mfma_f32_16x16x32_bf16 v[248:251], v[208:211], v[88:91], v[248:251]
	ds_read_b128 v[244:247], v184 offset:320
	s_waitcnt lgkmcnt(6)
	v_mfma_f32_16x16x32_bf16 v[230:233], v[212:215], v[88:91], v[230:233]
	ds_read_b128 v[208:211], v185 offset:384
	s_waitcnt lgkmcnt(6)
	v_mfma_f32_16x16x32_bf16 v[248:251], v[216:219], v[84:87], v[248:251]
	ds_read_b128 v[212:215], v184 offset:384
	s_waitcnt lgkmcnt(6)
	v_mfma_f32_16x16x32_bf16 v[230:233], v[220:223], v[84:87], v[230:233]
	ds_read_b128 v[216:219], v185 offset:448
	s_waitcnt lgkmcnt(6)
	v_mfma_f32_16x16x32_bf16 v[248:251], v[224:227], v[80:83], v[248:251]
	ds_read_b128 v[220:223], v184 offset:448
	s_waitcnt lgkmcnt(6)
	v_mfma_f32_16x16x32_bf16 v[230:233], v[236:239], v[80:83], v[230:233]
	s_waitcnt lgkmcnt(5)
	v_mfma_f32_16x16x32_bf16 v[248:251], v[240:243], v[76:79], v[248:251]
	s_waitcnt lgkmcnt(4)
	v_mfma_f32_16x16x32_bf16 v[230:233], v[244:247], v[76:79], v[230:233]
	s_waitcnt lgkmcnt(3)
	v_mfma_f32_16x16x32_bf16 v[248:251], v[208:211], v[72:75], v[248:251]
	s_waitcnt lgkmcnt(2)
	v_mfma_f32_16x16x32_bf16 v[230:233], v[212:215], v[72:75], v[230:233]
	s_waitcnt lgkmcnt(1)
	v_mfma_f32_16x16x32_bf16 v[76:79], v[216:219], v[68:71], v[248:251]
	s_waitcnt lgkmcnt(0)
	v_mfma_f32_16x16x32_bf16 v[68:71], v[220:223], v[68:71], v[230:233]
	s_nop 7
	v_fma_f32 v74, v104, v76, v196
	v_fma_f32 v75, v105, v77, v197
	v_lshlrev_b32_e32 v77, 16, v134
	v_mul_f32_e32 v76, v75, v75
	v_fmac_f32_e32 v76, v74, v74
	v_mul_f32_e32 v74, v74, v77
	v_and_b32_e32 v77, 0xffff0000, v134
	v_mul_f32_e32 v75, v75, v77
	v_pk_fma_f32 v[72:73], v[106:107], v[78:79], v[198:199]
	v_cvt_pk_bf16_f32 v74, v74, v75
	v_lshlrev_b32_e32 v75, 16, v135
	v_fmac_f32_e32 v76, v72, v72
	v_mul_f32_e32 v72, v72, v75
	v_and_b32_e32 v75, 0xffff0000, v135
	v_fmac_f32_e32 v76, v73, v73
	v_mul_f32_e32 v73, v73, v75
	v_cvt_pk_bf16_f32 v75, v72, v73
	v_lshl_add_u64 v[72:73], s[56:57], 0, v[122:123]
	v_pk_fma_f32 v[68:69], v[104:105], v[68:69], v[192:193]
	global_store_dwordx2 v[72:73], v[74:75], off
	v_mul_f32_e32 v72, v69, v69
	v_lshlrev_b32_e32 v73, 16, v132
	v_fmac_f32_e32 v72, v68, v68
	v_mul_f32_e32 v68, v68, v73
	v_and_b32_e32 v73, 0xffff0000, v132
	v_mul_f32_e32 v69, v69, v73
	v_pk_fma_f32 v[70:71], v[106:107], v[70:71], v[194:195]
	v_cvt_pk_bf16_f32 v68, v68, v69
	v_lshlrev_b32_e32 v69, 16, v133
	v_fmac_f32_e32 v72, v70, v70
	v_mul_f32_e32 v69, v70, v69
	v_and_b32_e32 v70, 0xffff0000, v133
	v_mul_f32_e32 v70, v71, v70
	v_fmac_f32_e32 v72, v71, v71
	v_cvt_pk_bf16_f32 v69, v69, v70
	v_lshl_add_u64 v[70:71], s[56:57], 0, v[124:125]
	global_store_dwordx2 v[70:71], v[68:69], off
	v_and_b32_e32 v69, 64, v229
	v_xor_b32_e32 v68, 16, v229
	v_add_u32_e32 v69, 64, v69
	v_cmp_lt_i32_e64 s[0:1], v68, v69
	v_add_f32_e32 v72, v76, v72
	v_xor_b32_e32 v71, 32, v229
	v_cndmask_b32_e64 v68, v229, v68, s[0:1]
	v_lshlrev_b32_e32 v68, 2, v68
	ds_bpermute_b32 v70, v68, v72
	v_cmp_lt_i32_e64 s[0:1], v71, v69
	s_waitcnt lgkmcnt(0)
	v_add_f32_e32 v70, v72, v70
	v_cndmask_b32_e64 v69, v229, v71, s[0:1]
	v_lshlrev_b32_e32 v69, 2, v69
	ds_bpermute_b32 v71, v69, v70
	s_and_saveexec_b64 s[0:1], vcc
	s_cbranch_execz .LBB0_178
	s_waitcnt lgkmcnt(0)
	v_add_f32_e32 v72, v70, v71
	v_lshl_add_u64 v[70:71], v[120:121], 0, s[10:11]
	global_atomic_add_f32 v[70:71], v72, off
	s_branch .LBB0_178
; __device__ __forceinline__ void ret_phase(const Params& p, unsigned char* shm, float* rssq) {
;     ...
;     for (int ch = 0; ch < 64; ++ch) {
;         __syncthreads();
;         cg2[0] = pg[0]; cg2[1] = pg[1];
; #pragma unroll
;         for (int j = 0; j < 4; ++j) {
;             *(u32x4*)(Qs + (j * 16 + (tid >> 5)) * QS + (tid & 31) * 8) = pq[j];
;             *(u32x4*)(Ks + lane * QS + wid * 32 + j * 8) = pk[j];
;             const unsigned kw[4] = {pk[j].x, pk[j].y, pk[j].z, pk[j].w};
; #pragma unroll
;             for (int i = 0; i < 4; ++i) {
;                 KTs[(wid * 32 + j * 8 + 2 * i) * TS + lane] = (bf16_t)(kw[i] & 0xffffu);
;                 KTs[(wid * 32 + j * 8 + 2 * i + 1) * TS + lane] = (bf16_t)(kw[i] >> 16);
;             }
;         }
;         { const unsigned vw[4] = {pv.x, pv.y, pv.z, pv.w};
; #pragma unroll
;           for (int i = 0; i < 4; ++i) { VTs[(wid * 8 + 2 * i) * TS + lane] = (bf16_t)(vw[i] & 0xffffu); VTs[(wid * 8 + 2 * i + 1) * TS + lane] = (bf16_t)(vw[i] >> 16); } }
; #pragma unroll
;         for (int ei = 0; ei < 4; ++ei)
; #pragma unroll
;             for (int di = 0; di < 2; ++di) { u32x2 w; w.x = cvt_pk_bf16(R[ei][di][0], R[ei][di][1]); w.y = cvt_pk_bf16(R[ei][di][2], R[ei][di][3]);
;                 *(u32x2*)(RTs + (16 * ei + fr) * QS + wid * 32 + 16 * di + 4 * fq) = w; }
;         if (ch + 1 < 64) {
;             const size_t adv = (size_t)(ch + 1) * 64 * 12288;
; #pragma unroll
;             for (int j = 0; j < 4; ++j) { pq[j] = *(const u32x4*)(qsrc + adv + (size_t)j * 16 * 12288); pk[j] = *(const u32x4*)(ksrc + adv + j * 8); }
;             pv = *(const u32x4*)(vsrc + adv);
;             pg[0] = *(const u32x2*)(gsrc + adv); pg[1] = *(const u32x2*)(gsrc + adv + 16);
;         }
;         __syncthreads();
;         bf16x8 qa[8];
;         {
;             f32x4 sacc[2] = {{0.f, 0.f, 0.f, 0.f}, {0.f, 0.f, 0.f, 0.f}};
; #pragma unroll
;             for (int ks = 0; ks < 8; ++ks) qa[ks] = *(const bf16x8*)(Qs + (16 * mi + fr) * QS + ks * 32 + fq * 8);
; #pragma unroll
;             for (int ks = 0; ks < 8; ++ks) {
; #pragma unroll
;                 for (int t = 0; t < 2; ++t) { const bf16x8 bf = *(const bf16x8*)(Ks + (16 * (ni0 + t) + fr) * QS + ks * 32 + fq * 8);
;                     sacc[t] = __builtin_amdgcn_mfma_f32_16x16x32_bf16(bf, qa[ks], sacc[t], 0, 0, 0); }
;             }
; #pragma unroll
.LBB0_181:
	s_barrier
	s_waitcnt vmcnt(3)
	ds_write_b128 v179, v[16:19]
	ds_write_b128 v150, v[28:31] offset:33792
	ds_write_b16 v151, v28
	ds_write_b16_d16_hi v175, v28 offset:144
	ds_write_b16 v151, v29 offset:288
	ds_write_b16_d16_hi v174, v29 offset:144
	ds_write_b16 v151, v30 offset:576
	ds_write_b16_d16_hi v173, v30 offset:144
	ds_write_b16 v151, v31 offset:864
	ds_write_b16_d16_hi v171, v31 offset:144
	ds_write_b128 v179, v[36:39] offset:8448
	ds_write_b128 v150, v[12:15] offset:33808
	ds_write_b16 v151, v12 offset:1152
	ds_write_b16_d16_hi v170, v12 offset:144
	ds_write_b16 v151, v13 offset:1440
	ds_write_b16_d16_hi v169, v13 offset:144
	ds_write_b16 v151, v14 offset:1728
	ds_write_b16_d16_hi v167, v14 offset:144
	ds_write_b16 v151, v15 offset:2016
	ds_write_b16_d16_hi v166, v15 offset:144
	ds_write_b128 v179, v[32:35] offset:16896
	ds_write_b128 v150, v[8:11] offset:33824
	ds_write_b16 v151, v8 offset:2304
	ds_write_b16_d16_hi v164, v8 offset:144
	ds_write_b16 v151, v9 offset:2592
	ds_write_b16_d16_hi v163, v9 offset:144
	ds_write_b16 v151, v10 offset:2880
	ds_write_b16_d16_hi v162, v10 offset:144
	ds_write_b16 v151, v11 offset:3168
	ds_write_b16_d16_hi v161, v11 offset:144
	ds_write_b128 v179, v[24:27] offset:25344
	ds_write_b128 v150, v[4:7] offset:33840
	ds_write_b16 v151, v4 offset:3456
	ds_write_b16_d16_hi v159, v4 offset:144
	ds_write_b16 v151, v5 offset:3744
	ds_write_b16_d16_hi v157, v5 offset:144
	ds_write_b16 v151, v6 offset:4032
	ds_write_b16_d16_hi v155, v6 offset:144
	ds_write_b16 v151, v7 offset:4320
	ds_write_b16_d16_hi v153, v7 offset:144
	ds_write_b16 v152, v20
	ds_write_b16_d16_hi v160, v20 offset:144
	ds_write_b16 v152, v21 offset:288
	ds_write_b16_d16_hi v158, v21 offset:144
	ds_write_b16 v152, v22 offset:576
	ds_write_b16_d16_hi v156, v22 offset:144
	ds_write_b16 v152, v23 offset:864
	ds_write_b16_d16_hi v154, v23 offset:144
	v_cvt_pk_bf16_f32 v4, v52, v53
	v_cvt_pk_bf16_f32 v5, v54, v55
	ds_write_b64 v165, v[4:5]
	v_cvt_pk_bf16_f32 v4, v40, v41
	v_cvt_pk_bf16_f32 v5, v42, v43
	ds_write_b64 v165, v[4:5] offset:32
	v_cvt_pk_bf16_f32 v4, v56, v57
	v_cvt_pk_bf16_f32 v5, v58, v59
	ds_write_b64 v165, v[4:5] offset:8448
	v_cvt_pk_bf16_f32 v4, v44, v45
	v_cvt_pk_bf16_f32 v5, v46, v47
	ds_write_b64 v165, v[4:5] offset:8480
	v_cvt_pk_bf16_f32 v4, v60, v61
	v_cvt_pk_bf16_f32 v5, v62, v63
	ds_write_b64 v165, v[4:5] offset:16896
	v_cvt_pk_bf16_f32 v4, v48, v49
	v_cvt_pk_bf16_f32 v5, v50, v51
	ds_write_b64 v165, v[4:5] offset:16928
	v_cvt_pk_bf16_f32 v4, v64, v65
	v_cvt_pk_bf16_f32 v5, v66, v67
	ds_write_b64 v165, v[4:5] offset:25344
	v_cvt_pk_bf16_f32 v0, v0, v1
	v_cvt_pk_bf16_f32 v1, v2, v3
	ds_write_b64 v165, v[0:1] offset:25376
	s_waitcnt lgkmcnt(0)
	s_barrier
	ds_read_b128 v[0:3], v183 offset:33792
	ds_read_b128 v[4:7], v149
	ds_read_b128 v[8:11], v149 offset:64
	ds_read_b128 v[12:15], v183 offset:33856
	s_waitcnt lgkmcnt(2)
	v_mfma_f32_16x16x32_bf16 v[0:3], v[0:3], v[4:7], 0
	ds_read_b128 v[16:19], v182 offset:33792
	ds_read_b128 v[20:23], v182 offset:33856
	v_or_b32_e32 v102, v102, v100
	s_lshl_b32 s0, s46, 1
	s_waitcnt lgkmcnt(2)
	v_mfma_f32_16x16x32_bf16 v[0:3], v[12:15], v[8:11], v[0:3]
	ds_read_b128 v[12:15], v183 offset:33920
	s_add_u32 s0, s34, s0
	s_addc_u32 s1, s35, 0
	s_waitcnt lgkmcnt(2)
	v_mfma_f32_16x16x32_bf16 v[16:19], v[16:19], v[4:7], 0
	s_waitcnt lgkmcnt(1)
	v_mfma_f32_16x16x32_bf16 v[16:19], v[20:23], v[8:11], v[16:19]
	ds_read_b128 v[20:23], v149 offset:128
	ds_read_b128 v[24:27], v149 offset:192
	ds_read_b128 v[28:31], v183 offset:33984
	s_waitcnt lgkmcnt(2)
	v_mfma_f32_16x16x32_bf16 v[0:3], v[12:15], v[20:23], v[0:3]
	ds_read_b128 v[12:15], v182 offset:33920
	ds_read_b128 v[32:35], v182 offset:33984
	s_waitcnt lgkmcnt(1)
	v_mfma_f32_16x16x32_bf16 v[12:15], v[12:15], v[20:23], v[16:19]
	s_nop 2
	ds_read_b128 v[16:19], v183 offset:34048
	v_mfma_f32_16x16x32_bf16 v[0:3], v[28:31], v[24:27], v[0:3]
	s_waitcnt lgkmcnt(1)
	v_mfma_f32_16x16x32_bf16 v[12:15], v[32:35], v[24:27], v[12:15]
	ds_read_b128 v[28:31], v149 offset:256
	ds_read_b128 v[32:35], v149 offset:320
	ds_read_b128 v[36:39], v183 offset:34112
	s_waitcnt lgkmcnt(2)
	v_mfma_f32_16x16x32_bf16 v[0:3], v[16:19], v[28:31], v[0:3]
	ds_read_b128 v[16:19], v182 offset:34048
	ds_read_b128 v[40:43], v182 offset:34112
	s_waitcnt lgkmcnt(1)
	v_mfma_f32_16x16x32_bf16 v[12:15], v[16:19], v[28:31], v[12:15]
	ds_read_b128 v[16:19], v183 offset:34176
	v_mfma_f32_16x16x32_bf16 v[0:3], v[36:39], v[32:35], v[0:3]
	s_waitcnt lgkmcnt(1)
	v_mfma_f32_16x16x32_bf16 v[12:15], v[40:43], v[32:35], v[12:15]
	ds_read_b128 v[36:39], v149 offset:384
	ds_read_b128 v[40:43], v149 offset:448
	ds_read_b128 v[44:47], v183 offset:34240
	s_waitcnt lgkmcnt(2)
	v_mfma_f32_16x16x32_bf16 v[0:3], v[16:19], v[36:39], v[0:3]
	ds_read_b128 v[16:19], v182 offset:34176
	ds_read_b128 v[48:51], v182 offset:34240
	s_waitcnt lgkmcnt(1)
	v_mfma_f32_16x16x32_bf16 v[12:15], v[16:19], v[36:39], v[12:15]
	v_mfma_f32_16x16x32_bf16 v[0:3], v[44:47], v[40:43], v[0:3]
	s_waitcnt lgkmcnt(0)
	v_mfma_f32_16x16x32_bf16 v[12:15], v[48:51], v[40:43], v[12:15]
	s_nop 5
	v_mul_f32_e32 v0, v138, v0
	v_mul_f32_e32 v1, v139, v1
	v_cvt_pk_bf16_f32 v0, v0, v1
	v_mul_f32_e32 v1, v140, v2
	v_mul_f32_e32 v2, v141, v3
	v_cvt_pk_bf16_f32 v1, v1, v2
	ds_write_b64 v186, v[0:1]
	v_mul_f32_e32 v0, v142, v12
	v_mul_f32_e32 v1, v143, v13
	v_cvt_pk_bf16_f32 v0, v0, v1
	v_mul_f32_e32 v1, v144, v14
	v_mul_f32_e32 v2, v145, v15
	v_cvt_pk_bf16_f32 v1, v1, v2
	ds_write_b64 v148, v[0:1]
	s_waitcnt lgkmcnt(0)
	s_barrier
; __device__ __forceinline__ unsigned cvt_pk_bf16(float lo, float hi) { unsigned r; asm volatile("v_cvt_pk_bf16_f32 %0, %1, %2" : "=v"(r) : "v"(lo), "v"(hi)); return r; }
; __device__ __forceinline__ float bflo(unsigned w) { return __uint_as_float(w << 16); }
; __device__ __forceinline__ float bfhi(unsigned w) { return __uint_as_float(w & 0xffff0000u); }
; __device__ __forceinline__ void ret_phase(const Params& p, unsigned char* shm, float* rssq) {
;     ...
;         {
;             f32x4 oi[2] = {{0.f, 0.f, 0.f, 0.f}, {0.f, 0.f, 0.f, 0.f}}, oc[2] = {{0.f, 0.f, 0.f, 0.f}, {0.f, 0.f, 0.f, 0.f}};
; #pragma unroll
;             for (int ks = 0; ks < 2; ++ks) {
;                 const bf16x8 af = *(const bf16x8*)(Ss + (16 * mi + fr) * TS + ks * 32 + fq * 8);
; #pragma unroll
;                 for (int t = 0; t < 2; ++t) { const bf16x8 bf = *(const bf16x8*)(VTs + (16 * (ni0 + t) + fr) * TS + ks * 32 + fq * 8);
;                     oi[t] = __builtin_amdgcn_mfma_f32_16x16x32_bf16(bf, af, oi[t], 0, 0, 0); }
;             }
; #pragma unroll
;             for (int ks = 0; ks < 8; ++ks) {
; #pragma unroll
;                 for (int t = 0; t < 2; ++t) { const bf16x8 bf = *(const bf16x8*)(RTs + (16 * (ni0 + t) + fr) * QS + ks * 32 + fq * 8);
;                     oc[t] = __builtin_amdgcn_mfma_f32_16x16x32_bf16(bf, qa[ks], oc[t], 0, 0, 0); }
;             }
;             const size_t tok = tokb + (size_t)ch * 64 + 16 * mi + fr;
;             float sq = 0.f;
; #pragma unroll
;             for (int t = 0; t < 2; ++t) {
;                 const int e = sl * 64 + 16 * (ni0 + t) + 4 * fq;
;                 const u32x2 gw = cg2[t];
;                 f32x4 ov = oi[t] + oc[t] * qdec;
;                 sq += ov[0] * ov[0] + ov[1] * ov[1] + ov[2] * ov[2] + ov[3] * ov[3];
;                 u32x2 w; w.x = cvt_pk_bf16(ov[0] * bflo(gw.x), ov[1] * bfhi(gw.x)); w.y = cvt_pk_bf16(ov[2] * bflo(gw.y), ov[3] * bfhi(gw.y));
;                 *(u32x2*)(ao + tok * 4096 + h * 512 + e) = w;
;             }
;             sq += __shfl_xor(sq, 16); sq += __shfl_xor(sq, 32);
;             if (fq == 0) atomicAdd(rssq + (size_t)(sl * 4 + mi) * 0 + (size_t)sl * (T_ * 8) + tok * 8 + h, sq);
	ds_read_b128 v[0:3], v147
	ds_read_b128 v[12:15], v117
	ds_read_b128 v[16:19], v117 offset:64
	ds_read_b128 v[44:47], v147 offset:64
	ds_read_b128 v[48:51], v146
	ds_read_b128 v[52:55], v146 offset:64
	s_waitcnt lgkmcnt(4)
	v_mfma_f32_16x16x32_bf16 v[0:3], v[0:3], v[12:15], 0
	s_waitcnt lgkmcnt(1)
	v_mfma_f32_16x16x32_bf16 v[12:15], v[48:51], v[12:15], 0
	v_mfma_f32_16x16x32_bf16 v[44:47], v[44:47], v[16:19], v[0:3]
	s_waitcnt lgkmcnt(0)
	v_mfma_f32_16x16x32_bf16 v[12:15], v[52:55], v[16:19], v[12:15]
	s_nop 2
	ds_read_b128 v[0:3], v185
	ds_read_b128 v[16:19], v185 offset:64
	ds_read_b128 v[48:51], v184
	ds_read_b128 v[52:55], v184 offset:64
	s_waitcnt lgkmcnt(3)
	v_mfma_f32_16x16x32_bf16 v[0:3], v[0:3], v[4:7], 0
	s_waitcnt lgkmcnt(1)
	v_mfma_f32_16x16x32_bf16 v[4:7], v[48:51], v[4:7], 0
	v_mfma_f32_16x16x32_bf16 v[0:3], v[16:19], v[8:11], v[0:3]
	s_waitcnt lgkmcnt(0)
	v_mfma_f32_16x16x32_bf16 v[4:7], v[52:55], v[8:11], v[4:7]
	ds_read_b128 v[8:11], v185 offset:128
	ds_read_b128 v[16:19], v185 offset:192
	s_waitcnt lgkmcnt(1)
	v_mfma_f32_16x16x32_bf16 v[0:3], v[8:11], v[20:23], v[0:3]
	ds_read_b128 v[8:11], v184 offset:128
	ds_read_b128 v[48:51], v184 offset:192
	s_waitcnt lgkmcnt(1)
	v_mfma_f32_16x16x32_bf16 v[4:7], v[8:11], v[20:23], v[4:7]
	v_mfma_f32_16x16x32_bf16 v[0:3], v[16:19], v[24:27], v[0:3]
	ds_read_b128 v[8:11], v185 offset:256
	ds_read_b128 v[16:19], v185 offset:320
	s_waitcnt lgkmcnt(2)
	v_mfma_f32_16x16x32_bf16 v[4:7], v[48:51], v[24:27], v[4:7]
	v_lshl_add_u64 v[24:25], s[6:7], 0, v[102:103]
	s_mov_b64 s[6:7], 0xfc0
	v_or_b32_e32 v26, s16, v136
	s_waitcnt lgkmcnt(1)
	v_mfma_f32_16x16x32_bf16 v[0:3], v[8:11], v[28:31], v[0:3]
	ds_read_b128 v[8:11], v184 offset:256
	ds_read_b128 v[20:23], v184 offset:320
	s_waitcnt lgkmcnt(1)
	v_mfma_f32_16x16x32_bf16 v[4:7], v[8:11], v[28:31], v[4:7]
	ds_read_b128 v[8:11], v185 offset:384
	v_mfma_f32_16x16x32_bf16 v[0:3], v[16:19], v[32:35], v[0:3]
	s_waitcnt lgkmcnt(1)
	v_mfma_f32_16x16x32_bf16 v[4:7], v[20:23], v[32:35], v[4:7]
	ds_read_b128 v[16:19], v184 offset:384
	ds_read_b128 v[20:23], v185 offset:448
	s_waitcnt lgkmcnt(2)
	v_mfma_f32_16x16x32_bf16 v[0:3], v[8:11], v[36:39], v[0:3]
	ds_read_b128 v[8:11], v184 offset:448
	s_waitcnt lgkmcnt(2)
	v_mfma_f32_16x16x32_bf16 v[4:7], v[16:19], v[36:39], v[4:7]
	s_waitcnt lgkmcnt(1)
	v_mfma_f32_16x16x32_bf16 v[16:19], v[20:23], v[40:43], v[0:3]
	v_or_b32_e32 v20, v26, v101
	v_lshlrev_b32_e32 v188, 1, v20
	v_or_b32_e32 v21, v137, v26
	s_waitcnt lgkmcnt(0)
	v_mfma_f32_16x16x32_bf16 v[2:5], v[8:11], v[40:43], v[4:7]
	v_lshl_add_u64 v[0:1], v[24:25], 0, s[6:7]
	s_nop 1
	v_pk_fma_f32 v[10:11], v[104:105], v[16:17], v[44:45]
	v_lshlrev_b32_e32 v17, 16, v110
	v_mul_f32_e32 v16, v11, v11
	v_fmac_f32_e32 v16, v10, v10
	v_mul_f32_e32 v10, v10, v17
	v_and_b32_e32 v17, 0xffff0000, v110
	v_mul_f32_e32 v11, v11, v17
	v_pk_fma_f32 v[8:9], v[106:107], v[18:19], v[46:47]
	v_cvt_pk_bf16_f32 v10, v10, v11
	v_lshlrev_b32_e32 v11, 16, v111
	v_lshlrev_b64 v[6:7], 13, v[0:1]
	v_fmac_f32_e32 v16, v8, v8
	v_mul_f32_e32 v8, v8, v11
	v_and_b32_e32 v11, 0xffff0000, v111
	v_lshl_add_u64 v[6:7], s[0:1], 0, v[6:7]
	v_fmac_f32_e32 v16, v9, v9
	v_mul_f32_e32 v9, v9, v11
	v_cvt_pk_bf16_f32 v11, v8, v9
	v_lshl_add_u64 v[8:9], v[6:7], 0, v[188:189]
	v_pk_fma_f32 v[2:3], v[104:105], v[2:3], v[12:13]
	global_store_dwordx2 v[8:9], v[10:11], off
	v_mul_f32_e32 v8, v3, v3
	v_pk_fma_f32 v[4:5], v[106:107], v[4:5], v[14:15]
	v_fmac_f32_e32 v8, v2, v2
	v_fmac_f32_e32 v8, v4, v4
	v_fmac_f32_e32 v8, v5, v5
	v_add_f32_e32 v9, v16, v8
	v_lshlrev_b32_e32 v8, 16, v108
	v_mul_f32_e32 v2, v2, v8
	v_and_b32_e32 v8, 0xffff0000, v108
	v_mul_f32_e32 v3, v3, v8
	v_cvt_pk_bf16_f32 v8, v2, v3
	ds_bpermute_b32 v2, v68, v9
	v_lshlrev_b32_e32 v3, 16, v109
	v_mul_f32_e32 v4, v4, v3
	v_and_b32_e32 v3, 0xffff0000, v109
	v_mul_f32_e32 v5, v5, v3
	s_waitcnt lgkmcnt(0)
	v_add_f32_e32 v2, v9, v2
	ds_bpermute_b32 v3, v69, v2
	v_lshlrev_b32_e32 v188, 1, v21
	v_cvt_pk_bf16_f32 v9, v4, v5
	v_lshl_add_u64 v[4:5], v[6:7], 0, v[188:189]
	global_store_dwordx2 v[4:5], v[8:9], off
	s_and_saveexec_b64 s[0:1], vcc
	s_cbranch_execz .LBB0_183
	s_add_u32 s5, s5, s13
	s_addc_u32 s7, s14, 0
	s_lshl_b32 s6, s15, 2
	s_add_u32 s6, s5, s6
	s_addc_u32 s7, s7, 0
	v_lshlrev_b64 v[0:1], 5, v[0:1]
	s_waitcnt lgkmcnt(0)
	v_add_f32_e32 v2, v2, v3
	v_lshl_add_u64 v[0:1], s[6:7], 0, v[0:1]
	flat_atomic_add_f32 v[0:1], v2
